# B1 barrier + member spin with 4 polls in flight + accumulator zeroing with v_mov_b64
# speedup vs baseline: 1.0086x; 1.0086x over previous
.LBB0_115:
	s_lshl_b32 s2, s86, 8
	s_add_u32 s4, s84, s2
	s_addc_u32 s5, s85, 0
	v_mov_b32_e32 v3, 0x1000
	v_mov_b32_e32 v5, 1
	global_atomic_add v5, v3, v5, s[4:5] offset:1024 sc0
	v_cvt_f32_u32_e32 v3, v4
	v_sub_u32_e32 v6, 0, v4
	v_rcp_iflag_f32_e32 v3, v3
	s_nop 0
	v_mul_f32_e32 v3, 0x4f7ffffe, v3
	v_cvt_u32_f32_e32 v3, v3
	v_mul_lo_u32 v6, v6, v3
	v_mul_hi_u32 v6, v3, v6
	v_add_u32_e32 v3, v3, v6
	s_waitcnt vmcnt(0)
	v_mul_hi_u32 v3, v5, v3
	v_mul_lo_u32 v6, v3, v4
	v_sub_u32_e32 v6, v5, v6
	v_add_u32_e32 v7, 1, v3
	v_cmp_ge_u32_e32 vcc, v6, v4
	v_add_u32_e32 v5, 1, v5
	s_nop 0
	v_cndmask_b32_e32 v3, v3, v7, vcc
	v_sub_u32_e32 v7, v6, v4
	v_cndmask_b32_e32 v6, v6, v7, vcc
	v_add_u32_e32 v7, 1, v3
	v_cmp_ge_u32_e32 vcc, v6, v4
	s_nop 1
	v_cndmask_b32_e32 v3, v3, v7, vcc
	v_mul_lo_u32 v6, v4, v3
	v_add_u32_e32 v4, v6, v4
	v_cmp_ne_u32_e32 vcc, v5, v4
	s_and_saveexec_b64 s[2:3], vcc
	s_xor_b64 s[6:7], exec, s[2:3]
	s_cbranch_execz .LBB0_129
	s_waitcnt lgkmcnt(0)
	v_mov_b32_e32 v2, 0x2000
	global_load_dword v2, v2, s[4:5] offset:1024 sc1
	s_add_u32 s18, s4, 0x2400
	s_addc_u32 s19, s5, 0
	s_waitcnt vmcnt(0)
	v_cmp_eq_u32_e32 vcc, v2, v3
	s_and_saveexec_b64 s[12:13], vcc
	s_cbranch_execz .LBB0_128
	v_mov_b32_e32 v2, 0
	s_mov_b32 s2, 0
	global_load_dword v17, v2, s[18:19] sc1
	s_sleep 2
	global_load_dword v18, v2, s[18:19] sc1
	s_sleep 2
	global_load_dword v4, v2, s[18:19] sc1
	s_sleep 2
.Lpp_0:
	global_load_dword v5, v2, s[18:19] sc1
	s_waitcnt vmcnt(3)
	v_cmp_ne_u32_e32 vcc, v17, v3
	s_cbranch_vccnz .LBB0_128
	s_sleep 2
	global_load_dword v17, v2, s[18:19] sc1
	s_waitcnt vmcnt(3)
	v_cmp_ne_u32_e32 vcc, v18, v3
	s_cbranch_vccnz .LBB0_128
	s_sleep 2
	global_load_dword v18, v2, s[18:19] sc1
	s_waitcnt vmcnt(3)
	v_cmp_ne_u32_e32 vcc, v4, v3
	s_cbranch_vccnz .LBB0_128
	s_sleep 2
	global_load_dword v4, v2, s[18:19] sc1
	s_waitcnt vmcnt(3)
	v_cmp_ne_u32_e32 vcc, v5, v3
	s_cbranch_vccnz .LBB0_128
	s_sleep 2
	s_add_u32 s2, s2, 1
	s_cmp_lt_u32 s2, 0x100000
	s_cbranch_scc1 .Lpp_0

.LBB0_220:
	s_add_u32 s38, s38, 0x80080
	s_addc_u32 s39, s39, 0
	s_add_u32 s21, s40, 0x100
	v_mov_b32_e32 v2, 0
	s_addc_u32 s23, s41, 0
	s_mov_b32 s25, 0
	v_mov_b32_e32 v3, v2
	v_mov_b64_e32 v[4:5], v[2:3]
	v_mov_b64_e32 v[6:7], v[2:3]
	v_mov_b64_e32 v[8:9], v[2:3]
	v_mov_b64_e32 v[10:11], v[2:3]
	v_mov_b64_e32 v[12:13], v[2:3]
	v_mov_b64_e32 v[14:15], v[2:3]
	v_mov_b64_e32 v[16:17], v[2:3]
	v_mov_b64_e32 v[18:19], v[2:3]
	v_mov_b64_e32 v[20:21], v[2:3]
	v_mov_b64_e32 v[22:23], v[2:3]
	v_mov_b64_e32 v[24:25], v[2:3]
	v_mov_b64_e32 v[26:27], v[2:3]
	v_mov_b64_e32 v[28:29], v[2:3]
	v_mov_b64_e32 v[30:31], v[2:3]
	v_mov_b64_e32 v[32:33], v[2:3]
	v_mov_b64_e32 v[34:35], v[2:3]
	v_mov_b64_e32 v[36:37], v[2:3]
	v_mov_b64_e32 v[38:39], v[2:3]
	v_mov_b64_e32 v[40:41], v[2:3]
	v_mov_b64_e32 v[42:43], v[2:3]
	v_mov_b64_e32 v[44:45], v[2:3]
	v_mov_b64_e32 v[46:47], v[2:3]
	v_mov_b64_e32 v[48:49], v[2:3]
	v_mov_b64_e32 v[50:51], v[2:3]
	v_mov_b64_e32 v[52:53], v[2:3]
	v_mov_b64_e32 v[54:55], v[2:3]
	v_mov_b64_e32 v[56:57], v[2:3]
	v_mov_b64_e32 v[58:59], v[2:3]
	v_mov_b64_e32 v[60:61], v[2:3]
	v_mov_b64_e32 v[62:63], v[2:3]
	v_mov_b64_e32 v[64:65], v[2:3]
	v_mov_b64_e32 v[66:67], v[2:3]
	v_mov_b64_e32 v[68:69], v[2:3]
	v_mov_b64_e32 v[70:71], v[2:3]
	v_mov_b64_e32 v[72:73], v[2:3]
	v_mov_b64_e32 v[74:75], v[2:3]
	v_mov_b64_e32 v[76:77], v[2:3]
	v_mov_b64_e32 v[78:79], v[2:3]
	v_mov_b64_e32 v[80:81], v[2:3]
	v_mov_b64_e32 v[82:83], v[2:3]
	v_mov_b64_e32 v[84:85], v[2:3]
	v_mov_b64_e32 v[86:87], v[2:3]
	v_mov_b64_e32 v[88:89], v[2:3]
	v_mov_b64_e32 v[90:91], v[2:3]
	v_mov_b64_e32 v[92:93], v[2:3]
	v_mov_b64_e32 v[94:95], v[2:3]
	v_mov_b64_e32 v[96:97], v[2:3]
	v_mov_b64_e32 v[98:99], v[2:3]
	v_mov_b64_e32 v[100:101], v[2:3]
	v_mov_b64_e32 v[102:103], v[2:3]
	v_mov_b64_e32 v[104:105], v[2:3]
	v_mov_b64_e32 v[106:107], v[2:3]
	v_mov_b64_e32 v[108:109], v[2:3]
	v_mov_b64_e32 v[110:111], v[2:3]
	v_mov_b64_e32 v[112:113], v[2:3]
	v_mov_b64_e32 v[114:115], v[2:3]
	v_mov_b64_e32 v[116:117], v[2:3]
	v_mov_b64_e32 v[118:119], v[2:3]
	v_mov_b64_e32 v[120:121], v[2:3]
	v_mov_b64_e32 v[122:123], v[2:3]
	v_mov_b64_e32 v[124:125], v[2:3]
	v_mov_b64_e32 v[126:127], v[2:3]
	v_mov_b64_e32 v[128:129], v[2:3]

.LBB0_356:
	s_add_u32 s30, s30, 0x160080
	s_addc_u32 s31, s31, 0
	s_add_u32 s23, s34, 0x100
	v_mov_b32_e32 v2, 0
	s_addc_u32 s29, s35, 0
	s_mov_b32 s34, 0
	v_mov_b32_e32 v3, v2
	v_mov_b64_e32 v[4:5], v[2:3]
	v_mov_b64_e32 v[6:7], v[2:3]
	v_mov_b64_e32 v[8:9], v[2:3]
	v_mov_b64_e32 v[10:11], v[2:3]
	v_mov_b64_e32 v[12:13], v[2:3]
	v_mov_b64_e32 v[14:15], v[2:3]
	v_mov_b64_e32 v[16:17], v[2:3]
	v_mov_b64_e32 v[18:19], v[2:3]
	v_mov_b64_e32 v[20:21], v[2:3]
	v_mov_b64_e32 v[22:23], v[2:3]
	v_mov_b64_e32 v[24:25], v[2:3]
	v_mov_b64_e32 v[26:27], v[2:3]
	v_mov_b64_e32 v[28:29], v[2:3]
	v_mov_b64_e32 v[30:31], v[2:3]
	v_mov_b64_e32 v[32:33], v[2:3]
	v_mov_b64_e32 v[34:35], v[2:3]
	v_mov_b64_e32 v[36:37], v[2:3]
	v_mov_b64_e32 v[38:39], v[2:3]
	v_mov_b64_e32 v[40:41], v[2:3]
	v_mov_b64_e32 v[42:43], v[2:3]
	v_mov_b64_e32 v[44:45], v[2:3]
	v_mov_b64_e32 v[46:47], v[2:3]
	v_mov_b64_e32 v[48:49], v[2:3]
	v_mov_b64_e32 v[50:51], v[2:3]
	v_mov_b64_e32 v[52:53], v[2:3]
	v_mov_b64_e32 v[54:55], v[2:3]
	v_mov_b64_e32 v[56:57], v[2:3]
	v_mov_b64_e32 v[58:59], v[2:3]
	v_mov_b64_e32 v[60:61], v[2:3]
	v_mov_b64_e32 v[62:63], v[2:3]
	v_mov_b64_e32 v[64:65], v[2:3]
	v_mov_b64_e32 v[66:67], v[2:3]
	v_mov_b64_e32 v[68:69], v[2:3]
	v_mov_b64_e32 v[70:71], v[2:3]
	v_mov_b64_e32 v[72:73], v[2:3]
	v_mov_b64_e32 v[74:75], v[2:3]
	v_mov_b64_e32 v[76:77], v[2:3]
	v_mov_b64_e32 v[78:79], v[2:3]
	v_mov_b64_e32 v[80:81], v[2:3]
	v_mov_b64_e32 v[82:83], v[2:3]
	v_mov_b64_e32 v[84:85], v[2:3]
	v_mov_b64_e32 v[86:87], v[2:3]
	v_mov_b64_e32 v[88:89], v[2:3]
	v_mov_b64_e32 v[90:91], v[2:3]
	v_mov_b64_e32 v[92:93], v[2:3]
	v_mov_b64_e32 v[94:95], v[2:3]
	v_mov_b64_e32 v[96:97], v[2:3]
	v_mov_b64_e32 v[98:99], v[2:3]
	v_mov_b64_e32 v[100:101], v[2:3]
	v_mov_b64_e32 v[102:103], v[2:3]
	v_mov_b64_e32 v[104:105], v[2:3]
	v_mov_b64_e32 v[106:107], v[2:3]
	v_mov_b64_e32 v[108:109], v[2:3]
	v_mov_b64_e32 v[110:111], v[2:3]
	v_mov_b64_e32 v[112:113], v[2:3]
	v_mov_b64_e32 v[114:115], v[2:3]
	v_mov_b64_e32 v[116:117], v[2:3]
	v_mov_b64_e32 v[118:119], v[2:3]
	v_mov_b64_e32 v[120:121], v[2:3]
	v_mov_b64_e32 v[122:123], v[2:3]
	v_mov_b64_e32 v[124:125], v[2:3]
	v_mov_b64_e32 v[126:127], v[2:3]
	v_mov_b64_e32 v[128:129], v[2:3]

.LBB0_443:
	s_lshl_b32 s2, s86, 8
	s_add_u32 s4, s84, s2
	s_addc_u32 s5, s85, 0
	v_mov_b32_e32 v3, 0x1000
	v_mov_b32_e32 v5, 1
	global_atomic_add v5, v3, v5, s[4:5] offset:1024 sc0
	v_cvt_f32_u32_e32 v3, v4
	v_sub_u32_e32 v6, 0, v4
	v_rcp_iflag_f32_e32 v3, v3
	s_nop 0
	v_mul_f32_e32 v3, 0x4f7ffffe, v3
	v_cvt_u32_f32_e32 v3, v3
	v_mul_lo_u32 v6, v6, v3
	v_mul_hi_u32 v6, v3, v6
	v_add_u32_e32 v3, v3, v6
	s_waitcnt vmcnt(0)
	v_mul_hi_u32 v3, v5, v3
	v_mul_lo_u32 v6, v3, v4
	v_sub_u32_e32 v6, v5, v6
	v_add_u32_e32 v7, 1, v3
	v_cmp_ge_u32_e32 vcc, v6, v4
	v_add_u32_e32 v5, 1, v5
	s_nop 0
	v_cndmask_b32_e32 v3, v3, v7, vcc
	v_sub_u32_e32 v7, v6, v4
	v_cndmask_b32_e32 v6, v6, v7, vcc
	v_add_u32_e32 v7, 1, v3
	v_cmp_ge_u32_e32 vcc, v6, v4
	s_nop 1
	v_cndmask_b32_e32 v3, v3, v7, vcc
	v_mul_lo_u32 v6, v4, v3
	v_add_u32_e32 v4, v6, v4
	v_cmp_ne_u32_e32 vcc, v5, v4
	s_and_saveexec_b64 s[2:3], vcc
	s_xor_b64 s[6:7], exec, s[2:3]
	s_cbranch_execz .LBB0_457
	s_waitcnt lgkmcnt(0)
	v_mov_b32_e32 v2, 0x2000
	global_load_dword v2, v2, s[4:5] offset:1024 sc1
	s_add_u32 s12, s4, 0x2400
	s_addc_u32 s13, s5, 0
	s_waitcnt vmcnt(0)
	v_cmp_eq_u32_e32 vcc, v2, v3
	s_and_saveexec_b64 s[8:9], vcc
	s_cbranch_execz .LBB0_456
	v_mov_b32_e32 v2, 0
	s_mov_b32 s2, 0
	global_load_dword v17, v2, s[12:13] sc1
	s_sleep 2
	global_load_dword v18, v2, s[12:13] sc1
	s_sleep 2
	global_load_dword v4, v2, s[12:13] sc1
	s_sleep 2
.Lpp_5:
	global_load_dword v5, v2, s[12:13] sc1
	s_waitcnt vmcnt(3)
	v_cmp_ne_u32_e32 vcc, v17, v3
	s_cbranch_vccnz .LBB0_456
	s_sleep 2
	global_load_dword v17, v2, s[12:13] sc1
	s_waitcnt vmcnt(3)
	v_cmp_ne_u32_e32 vcc, v18, v3
	s_cbranch_vccnz .LBB0_456
	s_sleep 2
	global_load_dword v18, v2, s[12:13] sc1
	s_waitcnt vmcnt(3)
	v_cmp_ne_u32_e32 vcc, v4, v3
	s_cbranch_vccnz .LBB0_456
	s_sleep 2
	global_load_dword v4, v2, s[12:13] sc1
	s_waitcnt vmcnt(3)
	v_cmp_ne_u32_e32 vcc, v5, v3
	s_cbranch_vccnz .LBB0_456
	s_sleep 2
	s_add_u32 s2, s2, 1
	s_cmp_lt_u32 s2, 0x100000
	s_cbranch_scc1 .Lpp_5

.LBB0_540:
	s_ashr_i32 s21, s20, 31
	s_lshl_b64 s[28:29], s[20:21], 20
	v_readlane_b32 s30, v249, 50
	v_readlane_b32 s31, v249, 51
	s_add_u32 s28, s30, s28
	s_addc_u32 s29, s31, s29
	s_add_u32 s23, s34, 0xf00
	s_addc_u32 s21, s35, 0
	s_and_b64 s[30:31], s[24:25], exec
	s_cselect_b32 s21, s29, s21
	s_cselect_b32 s54, s28, s23
	s_ashr_i32 s23, s22, 31
	s_lshl_b64 s[30:31], s[22:23], 20
	s_add_u32 s30, s2, s30
	s_addc_u32 s31, s3, s31
	s_add_u32 s55, s36, 0xf00
	s_addc_u32 s23, s37, 0
	s_and_b64 s[38:39], s[24:25], exec
	s_cselect_b32 s23, s31, s23
	s_cselect_b32 s55, s30, s55
	s_add_u32 s34, s34, 0x80080
	s_addc_u32 s35, s35, 0
	s_add_u32 s56, s36, 0x100
	v_mov_b32_e32 v2, 0
	s_addc_u32 s57, s37, 0
	s_mov_b32 s58, -2
	v_mov_b32_e32 v3, v2
	v_mov_b64_e32 v[4:5], v[2:3]
	v_mov_b64_e32 v[6:7], v[2:3]
	v_mov_b64_e32 v[8:9], v[2:3]
	v_mov_b64_e32 v[10:11], v[2:3]
	v_mov_b64_e32 v[12:13], v[2:3]
	v_mov_b64_e32 v[14:15], v[2:3]
	v_mov_b64_e32 v[16:17], v[2:3]
	v_mov_b64_e32 v[18:19], v[2:3]
	v_mov_b64_e32 v[20:21], v[2:3]
	v_mov_b64_e32 v[22:23], v[2:3]
	v_mov_b64_e32 v[24:25], v[2:3]
	v_mov_b64_e32 v[26:27], v[2:3]
	v_mov_b64_e32 v[28:29], v[2:3]
	v_mov_b64_e32 v[30:31], v[2:3]
	v_mov_b64_e32 v[32:33], v[2:3]
	v_mov_b64_e32 v[34:35], v[2:3]
	v_mov_b64_e32 v[36:37], v[2:3]
	v_mov_b64_e32 v[38:39], v[2:3]
	v_mov_b64_e32 v[40:41], v[2:3]
	v_mov_b64_e32 v[42:43], v[2:3]
	v_mov_b64_e32 v[44:45], v[2:3]
	v_mov_b64_e32 v[46:47], v[2:3]
	v_mov_b64_e32 v[48:49], v[2:3]
	v_mov_b64_e32 v[50:51], v[2:3]
	v_mov_b64_e32 v[52:53], v[2:3]
	v_mov_b64_e32 v[54:55], v[2:3]
	v_mov_b64_e32 v[56:57], v[2:3]
	v_mov_b64_e32 v[58:59], v[2:3]
	v_mov_b64_e32 v[60:61], v[2:3]
	v_mov_b64_e32 v[62:63], v[2:3]
	v_mov_b64_e32 v[64:65], v[2:3]
	v_mov_b64_e32 v[66:67], v[2:3]
	v_mov_b64_e32 v[68:69], v[2:3]
	v_mov_b64_e32 v[70:71], v[2:3]
	v_mov_b64_e32 v[72:73], v[2:3]
	v_mov_b64_e32 v[74:75], v[2:3]
	v_mov_b64_e32 v[76:77], v[2:3]
	v_mov_b64_e32 v[78:79], v[2:3]
	v_mov_b64_e32 v[80:81], v[2:3]
	v_mov_b64_e32 v[82:83], v[2:3]
	v_mov_b64_e32 v[84:85], v[2:3]
	v_mov_b64_e32 v[86:87], v[2:3]
	v_mov_b64_e32 v[88:89], v[2:3]
	v_mov_b64_e32 v[90:91], v[2:3]
	v_mov_b64_e32 v[92:93], v[2:3]
	v_mov_b64_e32 v[94:95], v[2:3]
	v_mov_b64_e32 v[96:97], v[2:3]
	v_mov_b64_e32 v[98:99], v[2:3]
	v_mov_b64_e32 v[100:101], v[2:3]
	v_mov_b64_e32 v[102:103], v[2:3]
	v_mov_b64_e32 v[104:105], v[2:3]
	v_mov_b64_e32 v[106:107], v[2:3]
	v_mov_b64_e32 v[108:109], v[2:3]
	v_mov_b64_e32 v[110:111], v[2:3]
	v_mov_b64_e32 v[112:113], v[2:3]
	v_mov_b64_e32 v[114:115], v[2:3]
	v_mov_b64_e32 v[116:117], v[2:3]
	v_mov_b64_e32 v[118:119], v[2:3]
	v_mov_b64_e32 v[120:121], v[2:3]
	v_mov_b64_e32 v[122:123], v[2:3]
	v_mov_b64_e32 v[124:125], v[2:3]
	v_mov_b64_e32 v[126:127], v[2:3]
	v_mov_b64_e32 v[128:129], v[2:3]

.LBB0_645:
	s_lshl_b32 s2, s86, 8
	s_add_u32 s4, s84, s2
	s_addc_u32 s5, s85, 0
	v_mov_b32_e32 v2, 0x1000
	v_mov_b32_e32 v4, 1
	global_atomic_add v4, v2, v4, s[4:5] offset:1024 sc0
	v_cvt_f32_u32_e32 v2, v3
	v_sub_u32_e32 v5, 0, v3
	v_rcp_iflag_f32_e32 v2, v2
	s_nop 0
	v_mul_f32_e32 v2, 0x4f7ffffe, v2
	v_cvt_u32_f32_e32 v2, v2
	v_mul_lo_u32 v5, v5, v2
	v_mul_hi_u32 v5, v2, v5
	v_add_u32_e32 v2, v2, v5
	s_waitcnt vmcnt(0)
	v_mul_hi_u32 v2, v4, v2
	v_mul_lo_u32 v5, v2, v3
	v_sub_u32_e32 v5, v4, v5
	v_add_u32_e32 v6, 1, v2
	v_cmp_ge_u32_e32 vcc, v5, v3
	v_add_u32_e32 v4, 1, v4
	s_nop 0
	v_cndmask_b32_e32 v2, v2, v6, vcc
	v_sub_u32_e32 v6, v5, v3
	v_cndmask_b32_e32 v5, v5, v6, vcc
	v_add_u32_e32 v6, 1, v2
	v_cmp_ge_u32_e32 vcc, v5, v3
	s_nop 1
	v_cndmask_b32_e32 v2, v2, v6, vcc
	v_mul_lo_u32 v5, v3, v2
	v_add_u32_e32 v3, v5, v3
	v_cmp_ne_u32_e32 vcc, v4, v3
	s_and_saveexec_b64 s[2:3], vcc
	s_xor_b64 s[6:7], exec, s[2:3]
	s_cbranch_execz .LBB0_659
	s_waitcnt lgkmcnt(0)
	v_mov_b32_e32 v1, 0x2000
	global_load_dword v1, v1, s[4:5] offset:1024 sc1
	s_add_u32 s12, s4, 0x2400
	s_addc_u32 s13, s5, 0
	s_waitcnt vmcnt(0)
	v_cmp_eq_u32_e32 vcc, v1, v2
	s_and_saveexec_b64 s[8:9], vcc
	s_cbranch_execz .LBB0_658
	v_mov_b32_e32 v1, 0
	s_mov_b32 s2, 0
	global_load_dword v16, v1, s[12:13] sc1
	s_sleep 2
	global_load_dword v17, v1, s[12:13] sc1
	s_sleep 2
	global_load_dword v3, v1, s[12:13] sc1
	s_sleep 2
.Lpp_8:
	global_load_dword v4, v1, s[12:13] sc1
	s_waitcnt vmcnt(3)
	v_cmp_ne_u32_e32 vcc, v16, v2
	s_cbranch_vccnz .LBB0_658
	s_sleep 2
	global_load_dword v16, v1, s[12:13] sc1
	s_waitcnt vmcnt(3)
	v_cmp_ne_u32_e32 vcc, v17, v2
	s_cbranch_vccnz .LBB0_658
	s_sleep 2
	global_load_dword v17, v1, s[12:13] sc1
	s_waitcnt vmcnt(3)
	v_cmp_ne_u32_e32 vcc, v3, v2
	s_cbranch_vccnz .LBB0_658
	s_sleep 2
	global_load_dword v3, v1, s[12:13] sc1
	s_waitcnt vmcnt(3)
	v_cmp_ne_u32_e32 vcc, v4, v2
	s_cbranch_vccnz .LBB0_658
	s_sleep 2
	s_add_u32 s2, s2, 1
	s_cmp_lt_u32 s2, 0x100000
	s_cbranch_scc1 .Lpp_8

.LBB0_689:
	s_ashr_i32 s13, s12, 31
	s_lshl_b64 s[22:23], s[12:13], 18
	s_add_u32 s22, s2, s22
	s_addc_u32 s23, s3, s23
	s_add_u32 s17, s26, 0x300
	s_addc_u32 s13, s27, 0
	s_and_b64 s[24:25], s[20:21], exec
	s_cselect_b32 s13, s23, s13
	s_cselect_b32 s46, s22, s17
	s_ashr_i32 s17, s16, 31
	s_lshl_b64 s[24:25], s[16:17], 18
	s_add_u32 s24, s33, s24
	s_addc_u32 s25, s34, s25
	s_add_u32 s47, s28, 0x300
	s_addc_u32 s17, s29, 0
	s_and_b64 s[30:31], s[20:21], exec
	s_cselect_b32 s17, s25, s17
	s_cselect_b32 s47, s24, s47
	s_add_u32 s26, s26, 0x20080
	s_addc_u32 s27, s27, 0
	s_add_u32 s48, s28, 0x100
	v_mov_b32_e32 v2, 0
	s_addc_u32 s49, s29, 0
	s_mov_b32 s50, -2
	v_mov_b32_e32 v3, v2
	v_mov_b64_e32 v[4:5], v[2:3]
	v_mov_b64_e32 v[6:7], v[2:3]
	v_mov_b64_e32 v[8:9], v[2:3]
	v_mov_b64_e32 v[10:11], v[2:3]
	v_mov_b64_e32 v[12:13], v[2:3]
	v_mov_b64_e32 v[14:15], v[2:3]
	v_mov_b64_e32 v[16:17], v[2:3]
	v_mov_b64_e32 v[18:19], v[2:3]
	v_mov_b64_e32 v[20:21], v[2:3]
	v_mov_b64_e32 v[22:23], v[2:3]
	v_mov_b64_e32 v[24:25], v[2:3]
	v_mov_b64_e32 v[26:27], v[2:3]
	v_mov_b64_e32 v[28:29], v[2:3]
	v_mov_b64_e32 v[30:31], v[2:3]
	v_mov_b64_e32 v[32:33], v[2:3]
	v_mov_b64_e32 v[34:35], v[2:3]
	v_mov_b64_e32 v[36:37], v[2:3]
	v_mov_b64_e32 v[38:39], v[2:3]
	v_mov_b64_e32 v[40:41], v[2:3]
	v_mov_b64_e32 v[42:43], v[2:3]
	v_mov_b64_e32 v[44:45], v[2:3]
	v_mov_b64_e32 v[46:47], v[2:3]
	v_mov_b64_e32 v[48:49], v[2:3]
	v_mov_b64_e32 v[50:51], v[2:3]
	v_mov_b64_e32 v[52:53], v[2:3]
	v_mov_b64_e32 v[54:55], v[2:3]
	v_mov_b64_e32 v[56:57], v[2:3]
	v_mov_b64_e32 v[58:59], v[2:3]
	v_mov_b64_e32 v[60:61], v[2:3]
	v_mov_b64_e32 v[62:63], v[2:3]
	v_mov_b64_e32 v[64:65], v[2:3]
	v_mov_b64_e32 v[66:67], v[2:3]
	v_mov_b64_e32 v[68:69], v[2:3]
	v_mov_b64_e32 v[70:71], v[2:3]
	v_mov_b64_e32 v[72:73], v[2:3]
	v_mov_b64_e32 v[74:75], v[2:3]
	v_mov_b64_e32 v[76:77], v[2:3]
	v_mov_b64_e32 v[78:79], v[2:3]
	v_mov_b64_e32 v[80:81], v[2:3]
	v_mov_b64_e32 v[82:83], v[2:3]
	v_mov_b64_e32 v[84:85], v[2:3]
	v_mov_b64_e32 v[86:87], v[2:3]
	v_mov_b64_e32 v[88:89], v[2:3]
	v_mov_b64_e32 v[90:91], v[2:3]
	v_mov_b64_e32 v[92:93], v[2:3]
	v_mov_b64_e32 v[94:95], v[2:3]
	v_mov_b64_e32 v[96:97], v[2:3]
	v_mov_b64_e32 v[98:99], v[2:3]
	v_mov_b64_e32 v[100:101], v[2:3]
	v_mov_b64_e32 v[102:103], v[2:3]
	v_mov_b64_e32 v[104:105], v[2:3]
	v_mov_b64_e32 v[106:107], v[2:3]
	v_mov_b64_e32 v[108:109], v[2:3]
	v_mov_b64_e32 v[110:111], v[2:3]
	v_mov_b64_e32 v[112:113], v[2:3]
	v_mov_b64_e32 v[114:115], v[2:3]
	v_mov_b64_e32 v[116:117], v[2:3]
	v_mov_b64_e32 v[118:119], v[2:3]
	v_mov_b64_e32 v[120:121], v[2:3]
	v_mov_b64_e32 v[122:123], v[2:3]
	v_mov_b64_e32 v[124:125], v[2:3]
	v_mov_b64_e32 v[126:127], v[2:3]
	v_mov_b64_e32 v[128:129], v[2:3]

.LBB0_713:
	s_ashr_i32 s21, s20, 31
	s_lshl_b64 s[28:29], s[20:21], 18
	s_add_u32 s28, s2, s28
	s_addc_u32 s29, s3, s29
	s_add_u32 s25, s34, 0x300
	s_addc_u32 s21, s35, 0
	s_and_b64 s[30:31], s[22:23], exec
	s_cselect_b32 s21, s29, s21
	s_cselect_b32 s55, s28, s25
	s_ashr_i32 s25, s24, 31
	s_lshl_b64 s[30:31], s[24:25], 18
	s_add_u32 s30, s33, s30
	s_addc_u32 s31, s40, s31
	s_add_u32 s56, s36, 0x300
	s_addc_u32 s25, s37, 0
	s_and_b64 s[38:39], s[22:23], exec
	s_cselect_b32 s25, s31, s25
	s_cselect_b32 s56, s30, s56
	s_add_u32 s34, s34, 0x20080
	s_addc_u32 s35, s35, 0
	s_add_u32 s57, s36, 0x100
	v_mov_b32_e32 v2, 0
	s_addc_u32 s58, s37, 0
	s_mov_b32 s59, -2
	v_mov_b32_e32 v3, v2
	v_mov_b64_e32 v[4:5], v[2:3]
	v_mov_b64_e32 v[6:7], v[2:3]
	v_mov_b64_e32 v[8:9], v[2:3]
	v_mov_b64_e32 v[10:11], v[2:3]
	v_mov_b64_e32 v[12:13], v[2:3]
	v_mov_b64_e32 v[14:15], v[2:3]
	v_mov_b64_e32 v[16:17], v[2:3]
	v_mov_b64_e32 v[18:19], v[2:3]
	v_mov_b64_e32 v[20:21], v[2:3]
	v_mov_b64_e32 v[22:23], v[2:3]
	v_mov_b64_e32 v[24:25], v[2:3]
	v_mov_b64_e32 v[26:27], v[2:3]
	v_mov_b64_e32 v[28:29], v[2:3]
	v_mov_b64_e32 v[30:31], v[2:3]
	v_mov_b64_e32 v[32:33], v[2:3]
	v_mov_b64_e32 v[34:35], v[2:3]
	v_mov_b64_e32 v[36:37], v[2:3]
	v_mov_b64_e32 v[38:39], v[2:3]
	v_mov_b64_e32 v[40:41], v[2:3]
	v_mov_b64_e32 v[42:43], v[2:3]
	v_mov_b64_e32 v[44:45], v[2:3]
	v_mov_b64_e32 v[46:47], v[2:3]
	v_mov_b64_e32 v[48:49], v[2:3]
	v_mov_b64_e32 v[50:51], v[2:3]
	v_mov_b64_e32 v[52:53], v[2:3]
	v_mov_b64_e32 v[54:55], v[2:3]
	v_mov_b64_e32 v[56:57], v[2:3]
	v_mov_b64_e32 v[58:59], v[2:3]
	v_mov_b64_e32 v[60:61], v[2:3]
	v_mov_b64_e32 v[62:63], v[2:3]
	v_mov_b64_e32 v[64:65], v[2:3]
	v_mov_b64_e32 v[66:67], v[2:3]
	v_mov_b64_e32 v[68:69], v[2:3]
	v_mov_b64_e32 v[70:71], v[2:3]
	v_mov_b64_e32 v[72:73], v[2:3]
	v_mov_b64_e32 v[74:75], v[2:3]
	v_mov_b64_e32 v[76:77], v[2:3]
	v_mov_b64_e32 v[78:79], v[2:3]
	v_mov_b64_e32 v[80:81], v[2:3]
	v_mov_b64_e32 v[82:83], v[2:3]
	v_mov_b64_e32 v[84:85], v[2:3]
	v_mov_b64_e32 v[86:87], v[2:3]
	v_mov_b64_e32 v[88:89], v[2:3]
	v_mov_b64_e32 v[90:91], v[2:3]
	v_mov_b64_e32 v[92:93], v[2:3]
	v_mov_b64_e32 v[94:95], v[2:3]
	v_mov_b64_e32 v[96:97], v[2:3]
	v_mov_b64_e32 v[98:99], v[2:3]
	v_mov_b64_e32 v[100:101], v[2:3]
	v_mov_b64_e32 v[102:103], v[2:3]
	v_mov_b64_e32 v[104:105], v[2:3]
	v_mov_b64_e32 v[106:107], v[2:3]
	v_mov_b64_e32 v[108:109], v[2:3]
	v_mov_b64_e32 v[110:111], v[2:3]
	v_mov_b64_e32 v[112:113], v[2:3]
	v_mov_b64_e32 v[114:115], v[2:3]
	v_mov_b64_e32 v[116:117], v[2:3]
	v_mov_b64_e32 v[118:119], v[2:3]
	v_mov_b64_e32 v[120:121], v[2:3]
	v_mov_b64_e32 v[122:123], v[2:3]
	v_mov_b64_e32 v[124:125], v[2:3]
	v_mov_b64_e32 v[126:127], v[2:3]
	v_mov_b64_e32 v[128:129], v[2:3]

.LBB0_1121:
	s_add_u32 s34, s34, 0x80080
	s_addc_u32 s35, s35, 0
	s_add_u32 s17, s36, 0x100
	v_mov_b32_e32 v2, 0
	s_addc_u32 s19, s37, 0
	s_mov_b32 s21, 0
	v_mov_b32_e32 v3, v2
	v_mov_b64_e32 v[4:5], v[2:3]
	v_mov_b64_e32 v[6:7], v[2:3]
	v_mov_b64_e32 v[8:9], v[2:3]
	v_mov_b64_e32 v[10:11], v[2:3]
	v_mov_b64_e32 v[12:13], v[2:3]
	v_mov_b64_e32 v[14:15], v[2:3]
	v_mov_b64_e32 v[16:17], v[2:3]
	v_mov_b64_e32 v[18:19], v[2:3]
	v_mov_b64_e32 v[20:21], v[2:3]
	v_mov_b64_e32 v[22:23], v[2:3]
	v_mov_b64_e32 v[24:25], v[2:3]
	v_mov_b64_e32 v[26:27], v[2:3]
	v_mov_b64_e32 v[28:29], v[2:3]
	v_mov_b64_e32 v[30:31], v[2:3]
	v_mov_b64_e32 v[32:33], v[2:3]
	v_mov_b64_e32 v[34:35], v[2:3]
	v_mov_b64_e32 v[36:37], v[2:3]
	v_mov_b64_e32 v[38:39], v[2:3]
	v_mov_b64_e32 v[40:41], v[2:3]
	v_mov_b64_e32 v[42:43], v[2:3]
	v_mov_b64_e32 v[44:45], v[2:3]
	v_mov_b64_e32 v[46:47], v[2:3]
	v_mov_b64_e32 v[48:49], v[2:3]
	v_mov_b64_e32 v[50:51], v[2:3]
	v_mov_b64_e32 v[52:53], v[2:3]
	v_mov_b64_e32 v[54:55], v[2:3]
	v_mov_b64_e32 v[56:57], v[2:3]
	v_mov_b64_e32 v[58:59], v[2:3]
	v_mov_b64_e32 v[60:61], v[2:3]
	v_mov_b64_e32 v[62:63], v[2:3]
	v_mov_b64_e32 v[64:65], v[2:3]
	v_mov_b64_e32 v[66:67], v[2:3]
	v_mov_b64_e32 v[68:69], v[2:3]
	v_mov_b64_e32 v[70:71], v[2:3]
	v_mov_b64_e32 v[72:73], v[2:3]
	v_mov_b64_e32 v[74:75], v[2:3]
	v_mov_b64_e32 v[76:77], v[2:3]
	v_mov_b64_e32 v[78:79], v[2:3]
	v_mov_b64_e32 v[80:81], v[2:3]
	v_mov_b64_e32 v[82:83], v[2:3]
	v_mov_b64_e32 v[84:85], v[2:3]
	v_mov_b64_e32 v[86:87], v[2:3]
	v_mov_b64_e32 v[88:89], v[2:3]
	v_mov_b64_e32 v[90:91], v[2:3]
	v_mov_b64_e32 v[92:93], v[2:3]
	v_mov_b64_e32 v[94:95], v[2:3]
	v_mov_b64_e32 v[96:97], v[2:3]
	v_mov_b64_e32 v[98:99], v[2:3]
	v_mov_b64_e32 v[100:101], v[2:3]
	v_mov_b64_e32 v[102:103], v[2:3]
	v_mov_b64_e32 v[104:105], v[2:3]
	v_mov_b64_e32 v[106:107], v[2:3]
	v_mov_b64_e32 v[108:109], v[2:3]
	v_mov_b64_e32 v[110:111], v[2:3]
	v_mov_b64_e32 v[112:113], v[2:3]
	v_mov_b64_e32 v[114:115], v[2:3]
	v_mov_b64_e32 v[116:117], v[2:3]
	v_mov_b64_e32 v[118:119], v[2:3]
	v_mov_b64_e32 v[120:121], v[2:3]
	v_mov_b64_e32 v[122:123], v[2:3]
	v_mov_b64_e32 v[124:125], v[2:3]
	v_mov_b64_e32 v[126:127], v[2:3]
	v_mov_b64_e32 v[128:129], v[2:3]

.LBB0_1314:
	s_add_u32 s30, s30, 0x80080
	s_addc_u32 s31, s31, 0
	s_add_u32 s15, s34, 0x100
	v_mov_b32_e32 v2, 0
	s_addc_u32 s17, s35, 0
	s_mov_b32 s19, 0
	v_mov_b32_e32 v3, v2
	v_mov_b64_e32 v[4:5], v[2:3]
	v_mov_b64_e32 v[6:7], v[2:3]
	v_mov_b64_e32 v[8:9], v[2:3]
	v_mov_b64_e32 v[10:11], v[2:3]
	v_mov_b64_e32 v[12:13], v[2:3]
	v_mov_b64_e32 v[14:15], v[2:3]
	v_mov_b64_e32 v[16:17], v[2:3]
	v_mov_b64_e32 v[18:19], v[2:3]
	v_mov_b64_e32 v[20:21], v[2:3]
	v_mov_b64_e32 v[22:23], v[2:3]
	v_mov_b64_e32 v[24:25], v[2:3]
	v_mov_b64_e32 v[26:27], v[2:3]
	v_mov_b64_e32 v[28:29], v[2:3]
	v_mov_b64_e32 v[30:31], v[2:3]
	v_mov_b64_e32 v[32:33], v[2:3]
	v_mov_b64_e32 v[34:35], v[2:3]
	v_mov_b64_e32 v[36:37], v[2:3]
	v_mov_b64_e32 v[38:39], v[2:3]
	v_mov_b64_e32 v[40:41], v[2:3]
	v_mov_b64_e32 v[42:43], v[2:3]
	v_mov_b64_e32 v[44:45], v[2:3]
	v_mov_b64_e32 v[46:47], v[2:3]
	v_mov_b64_e32 v[48:49], v[2:3]
	v_mov_b64_e32 v[50:51], v[2:3]
	v_mov_b64_e32 v[52:53], v[2:3]
	v_mov_b64_e32 v[54:55], v[2:3]
	v_mov_b64_e32 v[56:57], v[2:3]
	v_mov_b64_e32 v[58:59], v[2:3]
	v_mov_b64_e32 v[60:61], v[2:3]
	v_mov_b64_e32 v[62:63], v[2:3]
	v_mov_b64_e32 v[64:65], v[2:3]
	v_mov_b64_e32 v[66:67], v[2:3]
	v_mov_b64_e32 v[68:69], v[2:3]
	v_mov_b64_e32 v[70:71], v[2:3]
	v_mov_b64_e32 v[72:73], v[2:3]
	v_mov_b64_e32 v[74:75], v[2:3]
	v_mov_b64_e32 v[76:77], v[2:3]
	v_mov_b64_e32 v[78:79], v[2:3]
	v_mov_b64_e32 v[80:81], v[2:3]
	v_mov_b64_e32 v[82:83], v[2:3]
	v_mov_b64_e32 v[84:85], v[2:3]
	v_mov_b64_e32 v[86:87], v[2:3]
	v_mov_b64_e32 v[88:89], v[2:3]
	v_mov_b64_e32 v[90:91], v[2:3]
	v_mov_b64_e32 v[92:93], v[2:3]
	v_mov_b64_e32 v[94:95], v[2:3]
	v_mov_b64_e32 v[96:97], v[2:3]
	v_mov_b64_e32 v[98:99], v[2:3]
	v_mov_b64_e32 v[100:101], v[2:3]
	v_mov_b64_e32 v[102:103], v[2:3]
	v_mov_b64_e32 v[104:105], v[2:3]
	v_mov_b64_e32 v[106:107], v[2:3]
	v_mov_b64_e32 v[108:109], v[2:3]
	v_mov_b64_e32 v[110:111], v[2:3]
	v_mov_b64_e32 v[112:113], v[2:3]
	v_mov_b64_e32 v[114:115], v[2:3]
	v_mov_b64_e32 v[116:117], v[2:3]
	v_mov_b64_e32 v[118:119], v[2:3]
	v_mov_b64_e32 v[120:121], v[2:3]
	v_mov_b64_e32 v[122:123], v[2:3]
	v_mov_b64_e32 v[124:125], v[2:3]
	v_mov_b64_e32 v[126:127], v[2:3]
	v_mov_b64_e32 v[128:129], v[2:3]

.LBB0_1450:
	s_add_u32 s24, s24, 0x160080
	s_addc_u32 s25, s25, 0
	s_add_u32 s17, s26, 0x100
	v_mov_b32_e32 v2, 0
	s_addc_u32 s23, s27, 0
	s_mov_b32 s26, 0
	v_mov_b32_e32 v3, v2
	v_mov_b64_e32 v[4:5], v[2:3]
	v_mov_b64_e32 v[6:7], v[2:3]
	v_mov_b64_e32 v[8:9], v[2:3]
	v_mov_b64_e32 v[10:11], v[2:3]
	v_mov_b64_e32 v[12:13], v[2:3]
	v_mov_b64_e32 v[14:15], v[2:3]
	v_mov_b64_e32 v[16:17], v[2:3]
	v_mov_b64_e32 v[18:19], v[2:3]
	v_mov_b64_e32 v[20:21], v[2:3]
	v_mov_b64_e32 v[22:23], v[2:3]
	v_mov_b64_e32 v[24:25], v[2:3]
	v_mov_b64_e32 v[26:27], v[2:3]
	v_mov_b64_e32 v[28:29], v[2:3]
	v_mov_b64_e32 v[30:31], v[2:3]
	v_mov_b64_e32 v[32:33], v[2:3]
	v_mov_b64_e32 v[34:35], v[2:3]
	v_mov_b64_e32 v[36:37], v[2:3]
	v_mov_b64_e32 v[38:39], v[2:3]
	v_mov_b64_e32 v[40:41], v[2:3]
	v_mov_b64_e32 v[42:43], v[2:3]
	v_mov_b64_e32 v[44:45], v[2:3]
	v_mov_b64_e32 v[46:47], v[2:3]
	v_mov_b64_e32 v[48:49], v[2:3]
	v_mov_b64_e32 v[50:51], v[2:3]
	v_mov_b64_e32 v[52:53], v[2:3]
	v_mov_b64_e32 v[54:55], v[2:3]
	v_mov_b64_e32 v[56:57], v[2:3]
	v_mov_b64_e32 v[58:59], v[2:3]
	v_mov_b64_e32 v[60:61], v[2:3]
	v_mov_b64_e32 v[62:63], v[2:3]
	v_mov_b64_e32 v[64:65], v[2:3]
	v_mov_b64_e32 v[66:67], v[2:3]
	v_mov_b64_e32 v[68:69], v[2:3]
	v_mov_b64_e32 v[70:71], v[2:3]
	v_mov_b64_e32 v[72:73], v[2:3]
	v_mov_b64_e32 v[74:75], v[2:3]
	v_mov_b64_e32 v[76:77], v[2:3]
	v_mov_b64_e32 v[78:79], v[2:3]
	v_mov_b64_e32 v[80:81], v[2:3]
	v_mov_b64_e32 v[82:83], v[2:3]
	v_mov_b64_e32 v[84:85], v[2:3]
	v_mov_b64_e32 v[86:87], v[2:3]
	v_mov_b64_e32 v[88:89], v[2:3]
	v_mov_b64_e32 v[90:91], v[2:3]
	v_mov_b64_e32 v[92:93], v[2:3]
	v_mov_b64_e32 v[94:95], v[2:3]
	v_mov_b64_e32 v[96:97], v[2:3]
	v_mov_b64_e32 v[98:99], v[2:3]
	v_mov_b64_e32 v[100:101], v[2:3]
	v_mov_b64_e32 v[102:103], v[2:3]
	v_mov_b64_e32 v[104:105], v[2:3]
	v_mov_b64_e32 v[106:107], v[2:3]
	v_mov_b64_e32 v[108:109], v[2:3]
	v_mov_b64_e32 v[110:111], v[2:3]
	v_mov_b64_e32 v[112:113], v[2:3]
	v_mov_b64_e32 v[114:115], v[2:3]
	v_mov_b64_e32 v[116:117], v[2:3]
	v_mov_b64_e32 v[118:119], v[2:3]
	v_mov_b64_e32 v[120:121], v[2:3]
	v_mov_b64_e32 v[122:123], v[2:3]
	v_mov_b64_e32 v[124:125], v[2:3]
	v_mov_b64_e32 v[126:127], v[2:3]
	v_mov_b64_e32 v[128:129], v[2:3]

.LBB0_1972:
	s_add_u32 s30, s30, 0x80080
	s_addc_u32 s31, s31, 0
	s_add_u32 s19, s34, 0x100
	v_mov_b32_e32 v2, 0
	s_addc_u32 s21, s35, 0
	s_mov_b32 s23, 0
	v_mov_b32_e32 v3, v2
	v_mov_b64_e32 v[4:5], v[2:3]
	v_mov_b64_e32 v[6:7], v[2:3]
	v_mov_b64_e32 v[8:9], v[2:3]
	v_mov_b64_e32 v[10:11], v[2:3]
	v_mov_b64_e32 v[12:13], v[2:3]
	v_mov_b64_e32 v[14:15], v[2:3]
	v_mov_b64_e32 v[16:17], v[2:3]
	v_mov_b64_e32 v[18:19], v[2:3]
	v_mov_b64_e32 v[20:21], v[2:3]
	v_mov_b64_e32 v[22:23], v[2:3]
	v_mov_b64_e32 v[24:25], v[2:3]
	v_mov_b64_e32 v[26:27], v[2:3]
	v_mov_b64_e32 v[28:29], v[2:3]
	v_mov_b64_e32 v[30:31], v[2:3]
	v_mov_b64_e32 v[32:33], v[2:3]
	v_mov_b64_e32 v[34:35], v[2:3]
	v_mov_b64_e32 v[36:37], v[2:3]
	v_mov_b64_e32 v[38:39], v[2:3]
	v_mov_b64_e32 v[40:41], v[2:3]
	v_mov_b64_e32 v[42:43], v[2:3]
	v_mov_b64_e32 v[44:45], v[2:3]
	v_mov_b64_e32 v[46:47], v[2:3]
	v_mov_b64_e32 v[48:49], v[2:3]
	v_mov_b64_e32 v[50:51], v[2:3]
	v_mov_b64_e32 v[52:53], v[2:3]
	v_mov_b64_e32 v[54:55], v[2:3]
	v_mov_b64_e32 v[56:57], v[2:3]
	v_mov_b64_e32 v[58:59], v[2:3]
	v_mov_b64_e32 v[60:61], v[2:3]
	v_mov_b64_e32 v[62:63], v[2:3]
	v_mov_b64_e32 v[64:65], v[2:3]
	v_mov_b64_e32 v[66:67], v[2:3]
	v_mov_b64_e32 v[68:69], v[2:3]
	v_mov_b64_e32 v[70:71], v[2:3]
	v_mov_b64_e32 v[72:73], v[2:3]
	v_mov_b64_e32 v[74:75], v[2:3]
	v_mov_b64_e32 v[76:77], v[2:3]
	v_mov_b64_e32 v[78:79], v[2:3]
	v_mov_b64_e32 v[80:81], v[2:3]
	v_mov_b64_e32 v[82:83], v[2:3]
	v_mov_b64_e32 v[84:85], v[2:3]
	v_mov_b64_e32 v[86:87], v[2:3]
	v_mov_b64_e32 v[88:89], v[2:3]
	v_mov_b64_e32 v[90:91], v[2:3]
	v_mov_b64_e32 v[92:93], v[2:3]
	v_mov_b64_e32 v[94:95], v[2:3]
	v_mov_b64_e32 v[96:97], v[2:3]
	v_mov_b64_e32 v[98:99], v[2:3]
	v_mov_b64_e32 v[100:101], v[2:3]
	v_mov_b64_e32 v[102:103], v[2:3]
	v_mov_b64_e32 v[104:105], v[2:3]
	v_mov_b64_e32 v[106:107], v[2:3]
	v_mov_b64_e32 v[108:109], v[2:3]
	v_mov_b64_e32 v[110:111], v[2:3]
	v_mov_b64_e32 v[112:113], v[2:3]
	v_mov_b64_e32 v[114:115], v[2:3]
	v_mov_b64_e32 v[116:117], v[2:3]
	v_mov_b64_e32 v[118:119], v[2:3]
	v_mov_b64_e32 v[120:121], v[2:3]
	v_mov_b64_e32 v[122:123], v[2:3]
	v_mov_b64_e32 v[124:125], v[2:3]
	v_mov_b64_e32 v[126:127], v[2:3]
	v_mov_b64_e32 v[128:129], v[2:3]
